# KV/U (pn>=22) epilogue: 6 of 7 later part-row loads hoisted to the epilogue top (on v50)
# baseline (speedup 1.0000x reference)
.LBB0_481:
	s_lshl_b32 s4, s8, 8
	s_add_i32 s4, s4, s90
	v_or_b32_e32 v150, s4, v195
	s_mov_b64 s[8:9], -1
	s_cmp_lt_i32 s14, 22
	v_ashrrev_i32_e32 v151, 31, v150
	s_brev_b32 s50, 18
	s_mov_b32 s51, 0xfe5163ab
	s_cbranch_scc1 .LBB0_612
	v_lshlrev_b64 v[152:153], 6, v[150:151]
	v_lshl_add_u64 v[154:155], v[142:143], 0, v[152:153]
	global_load_dwordx4 v[222:225], v[154:155], off offset:1024
	global_load_dwordx4 v[234:237], v[154:155], off offset:2048
	global_load_dwordx4 v[238:241], v[154:155], off offset:3072
	v_add_co_u32_e32 v230, vcc, 0x2000, v154
	s_nop 1
	v_addc_co_u32_e32 v231, vcc, 0, v155, vcc
	global_load_dwordx4 v[242:245], v[230:231], off
	global_load_dwordx4 v[246:249], v[230:231], off offset:1024
	global_load_dwordx4 v[230:233], v[230:231], off offset:2048
	global_load_dwordx4 v[154:157], v[154:155], off
	s_cmp_gt_u32 s14, 24
	s_cselect_b64 s[12:13], -1, 0
	s_lshl_b32 s8, s14, 1
	s_ashr_i32 s4, s4, 12
	s_sub_i32 s17, s8, 50
	s_mul_i32 s4, s4, 6
	s_add_i32 s8, s4, s17
	s_mov_b64 s[40:41], -1
	s_waitcnt vmcnt(0)
	v_mov_b32_e32 v158, v155
	v_mov_b32_e32 v159, v156
	v_mov_b32_e32 v155, v157
	v_pk_add_f32 v[154:155], v[158:159], v[154:155]
	s_nop 0
	v_add_f32_e32 v154, v154, v155
	ds_bpermute_b32 v155, v197, v154
	s_waitcnt lgkmcnt(0)
	v_add_f32_e32 v154, v154, v155
	ds_bpermute_b32 v155, v198, v154
	s_waitcnt lgkmcnt(0)
	v_add_f32_e32 v154, v154, v155
	v_fmamk_f32 v154, v154, 0x3a800000, v216
	v_cmp_gt_f32_e32 vcc, s29, v154
	v_mul_f32_e32 v155, 0x4b800000, v154
	s_nop 0
	v_cndmask_b32_e32 v154, v154, v155, vcc
	v_rsq_f32_e32 v154, v154
	s_nop 0
	v_mul_f32_e32 v155, 0x45800000, v154
	v_cndmask_b32_e32 v154, v154, v155, vcc
	v_and_b32_e32 v155, 0xfcf, v150
	v_pk_mul_f32 v[174:175], v[126:127], v[154:155] op_sel_hi:[1,0]
	v_pk_mul_f32 v[176:177], v[124:125], v[154:155] op_sel_hi:[1,0]
	v_pk_mul_f32 v[170:171], v[122:123], v[154:155] op_sel_hi:[1,0]
	v_pk_mul_f32 v[172:173], v[120:121], v[154:155] op_sel_hi:[1,0]
	s_and_b64 vcc, exec, s[12:13]
	v_lshlrev_b32_e32 v158, 1, v155
	s_cbranch_vccz .LBB0_484
	s_ashr_i32 s9, s8, 31
	s_lshl_b64 s[24:25], s[8:9], 20
	v_lshl_add_u64 v[156:157], v[144:145], 0, s[24:25]
	v_mov_b32_e32 v159, v161
	v_lshl_add_u64 v[156:157], v[156:157], 0, v[158:159]
	v_add_co_u32_e32 v162, vcc, s68, v156
	v_cvt_pk_bf16_f32 v155, v176, v177
	s_nop 0
	v_addc_co_u32_e32 v163, vcc, 0, v157, vcc
	global_store_short_d16_hi v[162:163], v155, off
	v_add_co_u32_e32 v162, vcc, s69, v156
	v_cvt_pk_bf16_f32 v159, v174, v175
	s_nop 0
	v_addc_co_u32_e32 v163, vcc, 0, v157, vcc
	global_store_short v[162:163], v159, off
	v_add_co_u32_e32 v162, vcc, s70, v156
	v_cvt_pk_bf16_f32 v160, v172, v173
	s_nop 0
	v_addc_co_u32_e32 v163, vcc, 0, v157, vcc
	global_store_short_d16_hi v[162:163], v159, off
	v_add_co_u32_e32 v162, vcc, s71, v156
	global_store_short v[156:157], v155, off
	s_nop 0
	v_addc_co_u32_e32 v163, vcc, 0, v157, vcc
	global_store_short v[162:163], v160, off
	v_add_co_u32_e32 v162, vcc, 0xa000, v156
	v_cvt_pk_bf16_f32 v164, v170, v171
	s_nop 0
	v_addc_co_u32_e32 v163, vcc, 0, v157, vcc
	global_store_short_d16_hi v[162:163], v160, off
	v_add_co_u32_e32 v162, vcc, 0xc000, v156
	s_mov_b64 s[40:41], 0
	s_nop 0
	v_addc_co_u32_e32 v163, vcc, 0, v157, vcc
	v_add_co_u32_e32 v156, vcc, 0xe000, v156
	global_store_short v[162:163], v164, off
	s_nop 0
	v_addc_co_u32_e32 v157, vcc, 0, v157, vcc
	global_store_short_d16_hi v[156:157], v164, off

.LBB0_498:
	s_nop 1
	v_or_b32_e32 v154, 16, v150
	v_ashrrev_i32_e32 v155, 31, v154
	v_lshlrev_b64 v[152:153], 6, v[154:155]
	v_lshl_add_u64 v[156:157], v[142:143], 0, v[152:153]
	s_waitcnt lgkmcnt(0)
	v_mov_b32_e32 v156, v222
	v_mov_b32_e32 v157, v223
	v_mov_b32_e32 v158, v224
	v_mov_b32_e32 v159, v225
	s_movk_i32 s9, 0xfdf
	s_mov_b64 s[12:13], -1
	v_mov_b32_e32 v162, v157
	v_mov_b32_e32 v163, v158
	v_mov_b32_e32 v157, v159
	v_pk_add_f32 v[156:157], v[162:163], v[156:157]
	s_nop 0
	v_add_f32_e32 v155, v156, v157
	ds_bpermute_b32 v156, v197, v155
	s_waitcnt lgkmcnt(0)
	v_add_f32_e32 v155, v155, v156
	ds_bpermute_b32 v156, v198, v155
	s_waitcnt lgkmcnt(0)
	v_add_f32_e32 v155, v155, v156
	v_fmamk_f32 v155, v155, 0x3a800000, v216
	v_cmp_gt_f32_e32 vcc, s29, v155
	v_mul_f32_e32 v156, 0x4b800000, v155
	s_nop 0
	v_cndmask_b32_e32 v155, v155, v156, vcc
	v_rsq_f32_e32 v155, v155
	s_nop 0
	v_mul_f32_e32 v156, 0x45800000, v155
	v_cndmask_b32_e32 v156, v155, v156, vcc
	v_bitop3_b32 v155, v150, s9, 16 bitop3:0xc8
	v_pk_mul_f32 v[174:175], v[110:111], v[156:157] op_sel_hi:[1,0]
	v_pk_mul_f32 v[176:177], v[108:109], v[156:157] op_sel_hi:[1,0]
	v_pk_mul_f32 v[158:159], v[106:107], v[156:157] op_sel_hi:[1,0]
	v_pk_mul_f32 v[170:171], v[104:105], v[156:157] op_sel_hi:[1,0]
	s_and_b64 vcc, exec, s[42:43]
	v_lshlrev_b32_e32 v172, 1, v155
	s_cbranch_vccnz .LBB0_500
	s_ashr_i32 s9, s8, 31
	s_lshl_b64 s[12:13], s[8:9], 20
	v_lshl_add_u64 v[162:163], v[144:145], 0, s[12:13]
	v_mov_b32_e32 v173, v161
	v_lshl_add_u64 v[162:163], v[162:163], 0, v[172:173]
	v_add_co_u32_e32 v164, vcc, s68, v162
	v_cvt_pk_bf16_f32 v155, v176, v177
	s_nop 0
	v_addc_co_u32_e32 v165, vcc, 0, v163, vcc
	global_store_short_d16_hi v[164:165], v155, off
	v_add_co_u32_e32 v164, vcc, s69, v162
	v_cvt_pk_bf16_f32 v157, v174, v175
	s_nop 0
	v_addc_co_u32_e32 v165, vcc, 0, v163, vcc
	global_store_short v[164:165], v157, off
	v_add_co_u32_e32 v164, vcc, s70, v162
	v_cvt_pk_bf16_f32 v160, v170, v171
	s_nop 0
	v_addc_co_u32_e32 v165, vcc, 0, v163, vcc
	global_store_short_d16_hi v[164:165], v157, off
	v_add_co_u32_e32 v164, vcc, s71, v162
	global_store_short v[162:163], v155, off
	s_nop 0
	v_addc_co_u32_e32 v165, vcc, 0, v163, vcc
	global_store_short v[164:165], v160, off
	v_add_co_u32_e32 v164, vcc, 0xa000, v162
	v_cvt_pk_bf16_f32 v173, v158, v159
	s_nop 0
	v_addc_co_u32_e32 v165, vcc, 0, v163, vcc
	global_store_short_d16_hi v[164:165], v160, off
	v_add_co_u32_e32 v164, vcc, 0xc000, v162
	s_mov_b64 s[12:13], 0
	s_nop 0
	v_addc_co_u32_e32 v165, vcc, 0, v163, vcc
	v_add_co_u32_e32 v162, vcc, 0xe000, v162
	global_store_short v[164:165], v173, off
	s_nop 0
	v_addc_co_u32_e32 v163, vcc, 0, v163, vcc
	global_store_short_d16_hi v[162:163], v173, off

.LBB0_514:
	v_or_b32_e32 v154, 32, v150
	v_ashrrev_i32_e32 v155, 31, v154
	v_lshlrev_b64 v[152:153], 6, v[154:155]
	v_lshl_add_u64 v[156:157], v[142:143], 0, v[152:153]
	v_mov_b32_e32 v156, v234
	v_mov_b32_e32 v157, v235
	v_mov_b32_e32 v158, v236
	v_mov_b32_e32 v159, v237
	s_movk_i32 s9, 0xfef
	s_mov_b64 s[12:13], -1
	v_mov_b32_e32 v162, v157
	v_mov_b32_e32 v163, v158
	v_mov_b32_e32 v157, v159
	v_pk_add_f32 v[156:157], v[162:163], v[156:157]
	s_nop 0
	v_add_f32_e32 v155, v156, v157
	ds_bpermute_b32 v156, v197, v155
	s_waitcnt lgkmcnt(0)
	v_add_f32_e32 v155, v155, v156
	ds_bpermute_b32 v156, v198, v155
	s_waitcnt lgkmcnt(0)
	v_add_f32_e32 v155, v155, v156
	v_fmamk_f32 v155, v155, 0x3a800000, v216
	v_cmp_gt_f32_e32 vcc, s29, v155
	v_mul_f32_e32 v156, 0x4b800000, v155
	s_nop 0
	v_cndmask_b32_e32 v155, v155, v156, vcc
	v_rsq_f32_e32 v155, v155
	s_nop 0
	v_mul_f32_e32 v156, 0x45800000, v155
	v_cndmask_b32_e32 v156, v155, v156, vcc
	v_bitop3_b32 v155, v150, s9, 32 bitop3:0xc8
	v_pk_mul_f32 v[174:175], v[94:95], v[156:157] op_sel_hi:[1,0]
	v_pk_mul_f32 v[176:177], v[92:93], v[156:157] op_sel_hi:[1,0]
	v_pk_mul_f32 v[158:159], v[90:91], v[156:157] op_sel_hi:[1,0]
	v_pk_mul_f32 v[170:171], v[88:89], v[156:157] op_sel_hi:[1,0]
	s_and_b64 vcc, exec, s[42:43]
	v_lshlrev_b32_e32 v172, 1, v155
	s_cbranch_vccnz .LBB0_516
	s_ashr_i32 s9, s8, 31
	s_lshl_b64 s[12:13], s[8:9], 20
	v_lshl_add_u64 v[162:163], v[144:145], 0, s[12:13]
	v_mov_b32_e32 v173, v161
	v_lshl_add_u64 v[162:163], v[162:163], 0, v[172:173]
	v_add_co_u32_e32 v164, vcc, s68, v162
	v_cvt_pk_bf16_f32 v155, v176, v177
	s_nop 0
	v_addc_co_u32_e32 v165, vcc, 0, v163, vcc
	global_store_short_d16_hi v[164:165], v155, off
	v_add_co_u32_e32 v164, vcc, s69, v162
	v_cvt_pk_bf16_f32 v157, v174, v175
	s_nop 0
	v_addc_co_u32_e32 v165, vcc, 0, v163, vcc
	global_store_short v[164:165], v157, off
	v_add_co_u32_e32 v164, vcc, s70, v162
	v_cvt_pk_bf16_f32 v160, v170, v171
	s_nop 0
	v_addc_co_u32_e32 v165, vcc, 0, v163, vcc
	global_store_short_d16_hi v[164:165], v157, off
	v_add_co_u32_e32 v164, vcc, s71, v162
	global_store_short v[162:163], v155, off
	s_nop 0
	v_addc_co_u32_e32 v165, vcc, 0, v163, vcc
	global_store_short v[164:165], v160, off
	v_add_co_u32_e32 v164, vcc, 0xa000, v162
	v_cvt_pk_bf16_f32 v173, v158, v159
	s_nop 0
	v_addc_co_u32_e32 v165, vcc, 0, v163, vcc
	global_store_short_d16_hi v[164:165], v160, off
	v_add_co_u32_e32 v164, vcc, 0xc000, v162
	s_mov_b64 s[12:13], 0
	s_nop 0
	v_addc_co_u32_e32 v165, vcc, 0, v163, vcc
	v_add_co_u32_e32 v162, vcc, 0xe000, v162
	global_store_short v[164:165], v173, off
	s_nop 0
	v_addc_co_u32_e32 v163, vcc, 0, v163, vcc
	global_store_short_d16_hi v[162:163], v173, off

.LBB0_530:
	v_or_b32_e32 v154, 48, v150
	v_ashrrev_i32_e32 v155, 31, v154
	v_lshlrev_b64 v[152:153], 6, v[154:155]
	v_lshl_add_u64 v[156:157], v[142:143], 0, v[152:153]
	v_mov_b32_e32 v156, v238
	v_mov_b32_e32 v157, v239
	v_mov_b32_e32 v158, v240
	v_mov_b32_e32 v159, v241
	s_movk_i32 s9, 0xfff
	s_mov_b64 s[12:13], -1
	v_mov_b32_e32 v162, v157
	v_mov_b32_e32 v163, v158
	v_mov_b32_e32 v157, v159
	v_pk_add_f32 v[156:157], v[162:163], v[156:157]
	s_nop 0
	v_add_f32_e32 v155, v156, v157
	ds_bpermute_b32 v156, v197, v155
	s_waitcnt lgkmcnt(0)
	v_add_f32_e32 v155, v155, v156
	ds_bpermute_b32 v156, v198, v155
	s_waitcnt lgkmcnt(0)
	v_add_f32_e32 v155, v155, v156
	v_fmamk_f32 v155, v155, 0x3a800000, v216
	v_cmp_gt_f32_e32 vcc, s29, v155
	v_mul_f32_e32 v156, 0x4b800000, v155
	s_nop 0
	v_cndmask_b32_e32 v155, v155, v156, vcc
	v_rsq_f32_e32 v155, v155
	s_nop 0
	v_mul_f32_e32 v156, 0x45800000, v155
	v_cndmask_b32_e32 v156, v155, v156, vcc
	v_bitop3_b32 v155, v150, s9, 48 bitop3:0xc8
	v_pk_mul_f32 v[174:175], v[78:79], v[156:157] op_sel_hi:[1,0]
	v_pk_mul_f32 v[176:177], v[76:77], v[156:157] op_sel_hi:[1,0]
	v_pk_mul_f32 v[158:159], v[74:75], v[156:157] op_sel_hi:[1,0]
	v_pk_mul_f32 v[170:171], v[72:73], v[156:157] op_sel_hi:[1,0]
	s_and_b64 vcc, exec, s[42:43]
	v_lshlrev_b32_e32 v172, 1, v155
	s_cbranch_vccnz .LBB0_532
	s_ashr_i32 s9, s8, 31
	s_lshl_b64 s[12:13], s[8:9], 20
	v_lshl_add_u64 v[162:163], v[144:145], 0, s[12:13]
	v_mov_b32_e32 v173, v161
	v_lshl_add_u64 v[162:163], v[162:163], 0, v[172:173]
	v_add_co_u32_e32 v164, vcc, s68, v162
	v_cvt_pk_bf16_f32 v155, v176, v177
	s_nop 0
	v_addc_co_u32_e32 v165, vcc, 0, v163, vcc
	global_store_short_d16_hi v[164:165], v155, off
	v_add_co_u32_e32 v164, vcc, s69, v162
	v_cvt_pk_bf16_f32 v157, v174, v175
	s_nop 0
	v_addc_co_u32_e32 v165, vcc, 0, v163, vcc
	global_store_short v[164:165], v157, off
	v_add_co_u32_e32 v164, vcc, s70, v162
	v_cvt_pk_bf16_f32 v160, v170, v171
	s_nop 0
	v_addc_co_u32_e32 v165, vcc, 0, v163, vcc
	global_store_short_d16_hi v[164:165], v157, off
	v_add_co_u32_e32 v164, vcc, s71, v162
	global_store_short v[162:163], v155, off
	s_nop 0
	v_addc_co_u32_e32 v165, vcc, 0, v163, vcc
	global_store_short v[164:165], v160, off
	v_add_co_u32_e32 v164, vcc, 0xa000, v162
	v_cvt_pk_bf16_f32 v173, v158, v159
	s_nop 0
	v_addc_co_u32_e32 v165, vcc, 0, v163, vcc
	global_store_short_d16_hi v[164:165], v160, off
	v_add_co_u32_e32 v164, vcc, 0xc000, v162
	s_mov_b64 s[12:13], 0
	s_nop 0
	v_addc_co_u32_e32 v165, vcc, 0, v163, vcc
	v_add_co_u32_e32 v162, vcc, 0xe000, v162
	global_store_short v[164:165], v173, off
	s_nop 0
	v_addc_co_u32_e32 v163, vcc, 0, v163, vcc
	global_store_short_d16_hi v[162:163], v173, off

.LBB0_546:
	v_add_u32_e32 v158, 0x80, v150
	v_ashrrev_i32_e32 v159, 31, v158
	v_lshlrev_b64 v[156:157], 6, v[158:159]
	v_lshl_add_u64 v[154:155], v[142:143], 0, v[156:157]
	v_mov_b32_e32 v170, v242
	v_mov_b32_e32 v171, v243
	v_mov_b32_e32 v172, v244
	v_mov_b32_e32 v173, v245
	v_ashrrev_i32_e32 v152, 12, v158
	v_mad_i32_i24 v152, v152, 6, s17
	s_mov_b64 s[8:9], -1
	v_mov_b32_e32 v154, v171
	v_mov_b32_e32 v155, v172
	v_mov_b32_e32 v171, v173
	v_pk_add_f32 v[154:155], v[154:155], v[170:171]
	s_nop 0
	v_add_f32_e32 v153, v154, v155
	ds_bpermute_b32 v154, v197, v153
	v_and_b32_e32 v155, 0xfcf, v158
	v_lshlrev_b32_e32 v178, 1, v155
	s_waitcnt lgkmcnt(0)
	v_add_f32_e32 v153, v153, v154
	ds_bpermute_b32 v154, v198, v153
	s_waitcnt lgkmcnt(0)
	v_add_f32_e32 v153, v153, v154
	v_fmamk_f32 v153, v153, 0x3a800000, v216
	v_cmp_gt_f32_e32 vcc, s29, v153
	v_mul_f32_e32 v154, 0x4b800000, v153
	s_nop 0
	v_cndmask_b32_e32 v153, v153, v154, vcc
	v_rsq_f32_e32 v153, v153
	s_nop 0
	v_mul_f32_e32 v154, 0x45800000, v153
	v_cndmask_b32_e32 v154, v153, v154, vcc
	v_pk_mul_f32 v[174:175], v[62:63], v[154:155] op_sel_hi:[1,0]
	v_pk_mul_f32 v[176:177], v[60:61], v[154:155] op_sel_hi:[1,0]
	v_pk_mul_f32 v[170:171], v[58:59], v[154:155] op_sel_hi:[1,0]
	v_pk_mul_f32 v[172:173], v[56:57], v[154:155] op_sel_hi:[1,0]
	s_and_b64 vcc, exec, s[42:43]
	v_ashrrev_i32_e32 v153, 31, v152
	s_cbranch_vccnz .LBB0_548
	v_lshlrev_b64 v[162:163], 20, v[152:153]
	v_lshl_add_u64 v[162:163], v[144:145], 0, v[162:163]
	v_mov_b32_e32 v179, v161
	v_lshl_add_u64 v[162:163], v[162:163], 0, v[178:179]
	v_add_co_u32_e32 v164, vcc, s68, v162
	v_cvt_pk_bf16_f32 v155, v176, v177
	s_nop 0
	v_addc_co_u32_e32 v165, vcc, 0, v163, vcc
	global_store_short_d16_hi v[164:165], v155, off
	v_add_co_u32_e32 v164, vcc, s69, v162
	v_cvt_pk_bf16_f32 v159, v174, v175
	s_nop 0
	v_addc_co_u32_e32 v165, vcc, 0, v163, vcc
	global_store_short v[164:165], v159, off
	v_add_co_u32_e32 v164, vcc, s70, v162
	v_cvt_pk_bf16_f32 v160, v172, v173
	s_nop 0
	v_addc_co_u32_e32 v165, vcc, 0, v163, vcc
	global_store_short_d16_hi v[164:165], v159, off
	v_add_co_u32_e32 v164, vcc, s71, v162
	global_store_short v[162:163], v155, off
	s_nop 0
	v_addc_co_u32_e32 v165, vcc, 0, v163, vcc
	global_store_short v[164:165], v160, off
	v_add_co_u32_e32 v164, vcc, 0xa000, v162
	v_cvt_pk_bf16_f32 v179, v170, v171
	s_nop 0
	v_addc_co_u32_e32 v165, vcc, 0, v163, vcc
	global_store_short_d16_hi v[164:165], v160, off
	v_add_co_u32_e32 v164, vcc, 0xc000, v162
	s_mov_b64 s[8:9], 0
	s_nop 0
	v_addc_co_u32_e32 v165, vcc, 0, v163, vcc
	v_add_co_u32_e32 v162, vcc, 0xe000, v162
	global_store_short v[164:165], v179, off
	s_nop 0
	v_addc_co_u32_e32 v163, vcc, 0, v163, vcc
	global_store_short_d16_hi v[162:163], v179, off

.LBB0_562:
	v_add_u32_e32 v158, 0x90, v150
	v_ashrrev_i32_e32 v159, 31, v158
	v_lshlrev_b64 v[156:157], 6, v[158:159]
	v_lshl_add_u64 v[162:163], v[142:143], 0, v[156:157]
	v_mov_b32_e32 v170, v246
	v_mov_b32_e32 v171, v247
	v_mov_b32_e32 v172, v248
	v_mov_b32_e32 v173, v249
	s_mov_b64 s[8:9], -1
	v_mov_b32_e32 v162, v171
	v_mov_b32_e32 v163, v172
	v_mov_b32_e32 v171, v173
	v_pk_add_f32 v[162:163], v[162:163], v[170:171]
	s_nop 0
	v_add_f32_e32 v159, v162, v163
	ds_bpermute_b32 v160, v197, v159
	s_waitcnt lgkmcnt(0)
	v_add_f32_e32 v159, v159, v160
	ds_bpermute_b32 v160, v198, v159
	s_waitcnt lgkmcnt(0)
	v_add_f32_e32 v159, v159, v160
	v_fmamk_f32 v159, v159, 0x3a800000, v216
	v_cmp_gt_f32_e32 vcc, s29, v159
	v_mul_f32_e32 v160, 0x4b800000, v159
	s_nop 0
	v_cndmask_b32_e32 v159, v159, v160, vcc
	v_rsq_f32_e32 v159, v159
	s_nop 0
	v_mul_f32_e32 v160, 0x45800000, v159
	v_cndmask_b32_e32 v170, v159, v160, vcc
	v_and_b32_e32 v159, 0xfdf, v158
	v_pk_mul_f32 v[178:179], v[46:47], v[170:171] op_sel_hi:[1,0]
	v_pk_mul_f32 v[180:181], v[44:45], v[170:171] op_sel_hi:[1,0]
	v_pk_mul_f32 v[172:173], v[42:43], v[170:171] op_sel_hi:[1,0]
	v_pk_mul_f32 v[174:175], v[40:41], v[170:171] op_sel_hi:[1,0]
	s_and_b64 vcc, exec, s[42:43]
	v_lshlrev_b32_e32 v176, 1, v159
	s_cbranch_vccnz .LBB0_564
	v_lshlrev_b64 v[162:163], 20, v[152:153]
	v_lshl_add_u64 v[162:163], v[144:145], 0, v[162:163]
	v_mov_b32_e32 v177, v161
	v_lshl_add_u64 v[162:163], v[162:163], 0, v[176:177]
	v_add_co_u32_e32 v164, vcc, s68, v162
	v_cvt_pk_bf16_f32 v159, v180, v181
	s_nop 0
	v_addc_co_u32_e32 v165, vcc, 0, v163, vcc
	global_store_short_d16_hi v[164:165], v159, off
	v_add_co_u32_e32 v164, vcc, s69, v162
	v_cvt_pk_bf16_f32 v160, v178, v179
	s_nop 0
	v_addc_co_u32_e32 v165, vcc, 0, v163, vcc
	global_store_short v[164:165], v160, off
	v_add_co_u32_e32 v164, vcc, s70, v162
	v_cvt_pk_bf16_f32 v171, v174, v175
	s_nop 0
	v_addc_co_u32_e32 v165, vcc, 0, v163, vcc
	global_store_short_d16_hi v[164:165], v160, off
	v_add_co_u32_e32 v164, vcc, s71, v162
	global_store_short v[162:163], v159, off
	s_nop 0
	v_addc_co_u32_e32 v165, vcc, 0, v163, vcc
	global_store_short v[164:165], v171, off
	v_add_co_u32_e32 v164, vcc, 0xa000, v162
	v_cvt_pk_bf16_f32 v177, v172, v173
	s_nop 0
	v_addc_co_u32_e32 v165, vcc, 0, v163, vcc
	global_store_short_d16_hi v[164:165], v171, off
	v_add_co_u32_e32 v164, vcc, 0xc000, v162
	s_mov_b64 s[8:9], 0
	s_nop 0
	v_addc_co_u32_e32 v165, vcc, 0, v163, vcc
	v_add_co_u32_e32 v162, vcc, 0xe000, v162
	global_store_short v[164:165], v177, off
	s_nop 0
	v_addc_co_u32_e32 v163, vcc, 0, v163, vcc
	global_store_short_d16_hi v[162:163], v177, off

.LBB0_578:
	v_add_u32_e32 v158, 0xa0, v150
	v_ashrrev_i32_e32 v159, 31, v158
	v_lshlrev_b64 v[156:157], 6, v[158:159]
	v_lshl_add_u64 v[162:163], v[142:143], 0, v[156:157]
	v_mov_b32_e32 v170, v230
	v_mov_b32_e32 v171, v231
	v_mov_b32_e32 v172, v232
	v_mov_b32_e32 v173, v233
	s_mov_b64 s[8:9], -1
	v_mov_b32_e32 v162, v171
	v_mov_b32_e32 v163, v172
	v_mov_b32_e32 v171, v173
	v_pk_add_f32 v[162:163], v[162:163], v[170:171]
	s_nop 0
	v_add_f32_e32 v159, v162, v163
	ds_bpermute_b32 v160, v197, v159
	s_waitcnt lgkmcnt(0)
	v_add_f32_e32 v159, v159, v160
	ds_bpermute_b32 v160, v198, v159
	s_waitcnt lgkmcnt(0)
	v_add_f32_e32 v159, v159, v160
	v_fmamk_f32 v159, v159, 0x3a800000, v216
	v_cmp_gt_f32_e32 vcc, s29, v159
	v_mul_f32_e32 v160, 0x4b800000, v159
	s_nop 0
	v_cndmask_b32_e32 v159, v159, v160, vcc
	v_rsq_f32_e32 v159, v159
	s_nop 0
	v_mul_f32_e32 v160, 0x45800000, v159
	v_cndmask_b32_e32 v170, v159, v160, vcc
	v_and_b32_e32 v159, 0xfef, v158
	v_pk_mul_f32 v[178:179], v[30:31], v[170:171] op_sel_hi:[1,0]
	v_pk_mul_f32 v[180:181], v[28:29], v[170:171] op_sel_hi:[1,0]
	v_pk_mul_f32 v[172:173], v[26:27], v[170:171] op_sel_hi:[1,0]
	v_pk_mul_f32 v[174:175], v[24:25], v[170:171] op_sel_hi:[1,0]
	s_and_b64 vcc, exec, s[42:43]
	v_lshlrev_b32_e32 v176, 1, v159
	s_cbranch_vccnz .LBB0_580
	v_lshlrev_b64 v[162:163], 20, v[152:153]
	v_lshl_add_u64 v[162:163], v[144:145], 0, v[162:163]
	v_mov_b32_e32 v177, v161
	v_lshl_add_u64 v[162:163], v[162:163], 0, v[176:177]
	v_add_co_u32_e32 v164, vcc, s68, v162
	v_cvt_pk_bf16_f32 v159, v180, v181
	s_nop 0
	v_addc_co_u32_e32 v165, vcc, 0, v163, vcc
	global_store_short_d16_hi v[164:165], v159, off
	v_add_co_u32_e32 v164, vcc, s69, v162
	v_cvt_pk_bf16_f32 v160, v178, v179
	s_nop 0
	v_addc_co_u32_e32 v165, vcc, 0, v163, vcc
	global_store_short v[164:165], v160, off
	v_add_co_u32_e32 v164, vcc, s70, v162
	v_cvt_pk_bf16_f32 v171, v174, v175
	s_nop 0
	v_addc_co_u32_e32 v165, vcc, 0, v163, vcc
	global_store_short_d16_hi v[164:165], v160, off
	v_add_co_u32_e32 v164, vcc, s71, v162
	global_store_short v[162:163], v159, off
	s_nop 0
	v_addc_co_u32_e32 v165, vcc, 0, v163, vcc
	global_store_short v[164:165], v171, off
	v_add_co_u32_e32 v164, vcc, 0xa000, v162
	v_cvt_pk_bf16_f32 v177, v172, v173
	s_nop 0
	v_addc_co_u32_e32 v165, vcc, 0, v163, vcc
	global_store_short_d16_hi v[164:165], v171, off
	v_add_co_u32_e32 v164, vcc, 0xc000, v162
	s_mov_b64 s[8:9], 0
	s_nop 0
	v_addc_co_u32_e32 v165, vcc, 0, v163, vcc
	v_add_co_u32_e32 v162, vcc, 0xe000, v162
	global_store_short v[164:165], v177, off
	s_nop 0
	v_addc_co_u32_e32 v163, vcc, 0, v163, vcc
	global_store_short_d16_hi v[162:163], v177, off
